# RG-LRU gate epilogue scan pass: 64 row loads issued up front, per-step counted waits
# baseline (speedup 1.0000x reference)
; __device__ __forceinline__ float bf_lo(unsigned w) { return __uint_as_float(w << 16); }
; __device__ __forceinline__ float bf_hi(unsigned w) { return __uint_as_float(w & 0xffff0000u); }
;     __device__ __forceinline__ void operator()(const f32x4 (&acc)[2][2][4][2], const Unit& u, int wr, int wc, int fr, int fq) const {
;     ...
;             for (int j = 0; j < 4; ++j) sp[j] = 8.0f * softplus_neg(lv[j]);
; #pragma unroll
;             for (int ai = 0; ai < 2; ++ai)
; #pragma unroll
;                 for (int m = 0; m < 4; ++m) {
;                     const int row = row0 + ai * HALF + m * 16; const size_t off = (size_t)row * D + c0 + 4 * hf;
;                     const u32x2 xw = *(const u32x2*)(xrc + off); const float xr[4] = {bf_lo(xw.x), bf_hi(xw.x), bf_lo(xw.y), bf_hi(xw.y)};
;                     u32x4 w;
; #pragma unroll
;                     for (int j2 = 0; j2 < 2; ++j2) { const int j = 2 * j2;
;                         const f32x2v rp = (f32x2v){acc[ai][0][m][hf][j], acc[ai][0][m][hf][j + 1]} + (f32x2v){bav[j], bav[j + 1]}, ip = (f32x2v){acc[ai][1][m][hf][j], acc[ai][1][m][hf][j + 1]} + (f32x2v){biv[j], biv[j + 1]};
;                         const f32x2v er = rp * (-1.4426950408889634f), ei = ip * (-1.4426950408889634f);
;                         f32x2v tr, ti; tr.x = __builtin_amdgcn_exp2f(er.x); tr.y = __builtin_amdgcn_exp2f(er.y); ti.x = __builtin_amdgcn_exp2f(ei.x); ti.y = __builtin_amdgcn_exp2f(ei.y);
;                         const f32x2v dr = tr + 1.0f, di = ti + 1.0f; f32x2v r, ig; r.x = __builtin_amdgcn_rcpf(dr.x); r.y = __builtin_amdgcn_rcpf(dr.y); ig.x = __builtin_amdgcn_rcpf(di.x); ig.y = __builtin_amdgcn_rcpf(di.y);
;                         const f32x2v la = r * (f32x2v){-sp[j], -sp[j + 1]}, e2 = la * 2.8853900817779268f;
;                         f32x2v a2; a2.x = __builtin_amdgcn_exp2f(e2.x); a2.y = __builtin_amdgcn_exp2f(e2.y);
;                         const f32x2v om = __builtin_elementwise_max(1.0f - a2, (f32x2v){0.f, 0.f}); f32x2v mult; mult.x = __builtin_amdgcn_sqrtf(om.x); mult.y = __builtin_amdgcn_sqrtf(om.y);
;                         const f32x2v bt = (mult * ig) * (f32x2v){xr[j], xr[j + 1]};
;                         w[j] = pack_f16(la.x, bt.x); w[j + 1] = pack_f16(la.y, bt.y); }
;                     *(u32x4*)(AB + off) = w;
.LBB0_219:
	s_andn2_saveexec_b64 s[0:1], s[36:37]
	v_fmamk_f32 v75, v76, 0xbe800000, v249
	v_fma_f32 v75, -v76, v75, 0.5
	v_fma_f32 v75, -v76, v75, 1.0
	v_mul_f32_e32 v75, v76, v75
	s_or_b64 exec, exec, s[0:1]
	v_or_b32_e32 v152, 4, v152
	v_lshl_add_u64 v[76:77], v[152:153], 0, v[138:139]
	v_pk_add_f32 v[62:63], v[62:63], v[70:71]
	v_pk_add_f32 v[58:59], v[58:59], v[66:67]
	v_pk_mul_f32 v[62:63], v[62:63], s[88:89] op_sel_hi:[1,0]
	v_pk_mul_f32 v[58:59], v[58:59], s[88:89] op_sel_hi:[1,0]
	v_exp_f32_e32 v62, v62
	v_exp_f32_e32 v63, v63
	v_exp_f32_e32 v58, v58
	v_exp_f32_e32 v59, v59
	s_mov_b32 s0, 0xc1000000
	v_pk_add_f32 v[62:63], v[62:63], 1.0 op_sel_hi:[1,0]
	v_pk_add_f32 v[64:65], v[64:65], v[72:73]
	v_rcp_f32_e32 v62, v62
	v_rcp_f32_e32 v63, v63
	v_pk_add_f32 v[58:59], v[58:59], 1.0 op_sel_hi:[1,0]
	v_pk_mul_f32 v[64:65], v[64:65], s[88:89] op_sel_hi:[1,0]
	v_rcp_f32_e32 v86, v58
	v_rcp_f32_e32 v87, v59
	v_pk_mul_f32 v[58:59], v[80:81], s[0:1] op_sel_hi:[1,0]
	v_exp_f32_e32 v64, v64
	v_pk_mul_f32 v[62:63], v[62:63], v[58:59]
	v_exp_f32_e32 v65, v65
	v_pk_mul_f32 v[80:81], v[62:63], s[82:83] op_sel_hi:[1,0]
	v_cvt_f16_f32_e32 v62, v62
	v_exp_f32_e32 v80, v80
	v_exp_f32_e32 v81, v81
	v_pk_add_f32 v[60:61], v[60:61], v[68:69]
	v_cvt_f16_f32_e32 v63, v63
	v_pk_mul_f32 v[60:61], v[60:61], s[88:89] op_sel_hi:[1,0]
	v_pk_add_f32 v[80:81], v[80:81], 1.0 op_sel_hi:[1,0] neg_lo:[1,0] neg_hi:[1,0]
	v_exp_f32_e32 v60, v60
	v_max_f32_e32 v81, 0, v81
	v_max_f32_e32 v80, 0, v80
	v_sqrt_f32_e32 v80, v80
	v_sqrt_f32_e32 v81, v81
	v_exp_f32_e32 v61, v61
	v_pk_add_f32 v[64:65], v[64:65], 1.0 op_sel_hi:[1,0]
	v_pk_add_f32 v[54:55], v[54:55], v[70:71]
	v_pk_mul_f32 v[80:81], v[86:87], v[80:81]
	v_rcp_f32_e32 v64, v64
	v_rcp_f32_e32 v65, v65
	v_pk_add_f32 v[60:61], v[60:61], 1.0 op_sel_hi:[1,0]
	v_pk_mul_f32 v[54:55], v[54:55], s[88:89] op_sel_hi:[1,0]
	v_pk_add_f32 v[50:51], v[50:51], v[66:67]
	v_exp_f32_e32 v54, v54
	v_exp_f32_e32 v55, v55
	v_pk_mul_f32 v[50:51], v[50:51], s[88:89] op_sel_hi:[1,0]
	v_pk_add_f32 v[56:57], v[56:57], v[72:73]
	v_exp_f32_e32 v50, v50
	v_pk_add_f32 v[54:55], v[54:55], 1.0 op_sel_hi:[1,0]
	v_exp_f32_e32 v51, v51
	v_rcp_f32_e32 v54, v54
	v_rcp_f32_e32 v55, v55
	v_pk_add_f32 v[52:53], v[52:53], v[68:69]
	v_pk_add_f32 v[50:51], v[50:51], 1.0 op_sel_hi:[1,0]
	v_pk_mul_f32 v[52:53], v[52:53], s[88:89] op_sel_hi:[1,0]
	v_pk_mul_f32 v[54:55], v[54:55], v[58:59]
	v_rcp_f32_e32 v50, v50
	v_rcp_f32_e32 v51, v51
	v_exp_f32_e32 v52, v52
	v_exp_f32_e32 v53, v53
	v_pk_add_f32 v[46:47], v[46:47], v[70:71]
	v_pk_add_f32 v[42:43], v[42:43], v[66:67]
	v_pk_mul_f32 v[46:47], v[46:47], s[88:89] op_sel_hi:[1,0]
	v_pk_add_f32 v[52:53], v[52:53], 1.0 op_sel_hi:[1,0]
	v_exp_f32_e32 v46, v46
	v_rcp_f32_e32 v52, v52
	v_rcp_f32_e32 v53, v53
	v_exp_f32_e32 v47, v47
	v_pk_mul_f32 v[42:43], v[42:43], s[88:89] op_sel_hi:[1,0]
	v_pk_add_f32 v[48:49], v[48:49], v[72:73]
	v_exp_f32_e32 v42, v42
	v_pk_add_f32 v[46:47], v[46:47], 1.0 op_sel_hi:[1,0]
	v_exp_f32_e32 v43, v43
	v_rcp_f32_e32 v46, v46
	v_rcp_f32_e32 v47, v47
	v_pk_add_f32 v[44:45], v[44:45], v[68:69]
	v_pk_add_f32 v[42:43], v[42:43], 1.0 op_sel_hi:[1,0]
	v_pk_mul_f32 v[44:45], v[44:45], s[88:89] op_sel_hi:[1,0]
	v_pk_mul_f32 v[46:47], v[46:47], v[58:59]
	s_waitcnt lgkmcnt(0)
	v_lshlrev_b32_e32 v84, 16, v222
	v_and_b32_e32 v85, 0xffff0000, v222
	v_pk_mul_f32 v[80:81], v[80:81], v[84:85]
	v_lshlrev_b32_e32 v82, 16, v223
	v_cvt_f16_f32_sdwa v80, v80 dst_sel:WORD_1 dst_unused:UNUSED_PAD src0_sel:DWORD
	v_and_b32_e32 v83, 0xffff0000, v223
	v_rcp_f32_e32 v42, v42
	v_rcp_f32_e32 v43, v43
	v_or_b32_e32 v62, v80, v62
	v_cvt_f16_f32_sdwa v80, v81 dst_sel:WORD_1 dst_unused:UNUSED_PAD src0_sel:DWORD
	v_rcp_f32_e32 v81, v61
	v_exp_f32_e32 v44, v44
	v_exp_f32_e32 v45, v45
	v_or_b32_e32 v63, v80, v63
	v_rcp_f32_e32 v80, v60
	v_pk_mul_f32 v[60:61], v[74:75], s[0:1] op_sel_hi:[1,0]
	v_pk_add_f32 v[44:45], v[44:45], 1.0 op_sel_hi:[1,0]
	v_pk_mul_f32 v[64:65], v[64:65], v[60:61]
	v_rcp_f32_e32 v44, v44
	v_pk_mul_f32 v[74:75], v[64:65], s[82:83] op_sel_hi:[1,0]
	v_cvt_f16_f32_e32 v64, v64
	v_exp_f32_e32 v74, v74
	v_exp_f32_e32 v75, v75
	v_cvt_f16_f32_e32 v65, v65
	v_rcp_f32_e32 v45, v45
	v_pk_add_f32 v[38:39], v[38:39], v[70:71]
	v_pk_add_f32 v[74:75], v[74:75], 1.0 op_sel_hi:[1,0] neg_lo:[1,0] neg_hi:[1,0]
	v_pk_mul_f32 v[38:39], v[38:39], s[88:89] op_sel_hi:[1,0]
	v_max_f32_e32 v75, 0, v75
	v_max_f32_e32 v74, 0, v74
	v_sqrt_f32_e32 v74, v74
	v_sqrt_f32_e32 v75, v75
	v_exp_f32_e32 v38, v38
	v_exp_f32_e32 v39, v39
	v_pk_add_f32 v[34:35], v[34:35], v[66:67]
	v_pk_mul_f32 v[74:75], v[80:81], v[74:75]
	v_pk_mul_f32 v[34:35], v[34:35], s[88:89] op_sel_hi:[1,0]
	v_pk_mul_f32 v[74:75], v[74:75], v[82:83]
	v_pk_add_f32 v[38:39], v[38:39], 1.0 op_sel_hi:[1,0]
	v_cvt_f16_f32_sdwa v74, v74 dst_sel:WORD_1 dst_unused:UNUSED_PAD src0_sel:DWORD
	v_rcp_f32_e32 v38, v38
	v_rcp_f32_e32 v39, v39
	v_exp_f32_e32 v34, v34
	v_or_b32_e32 v64, v74, v64
	v_cvt_f16_f32_sdwa v74, v75 dst_sel:WORD_1 dst_unused:UNUSED_PAD src0_sel:DWORD
	v_pk_mul_f32 v[38:39], v[38:39], v[58:59]
	v_exp_f32_e32 v35, v35
	v_pk_add_f32 v[40:41], v[40:41], v[72:73]
	v_or_b32_e32 v65, v74, v65
	v_lshl_add_u64 v[74:75], v[76:77], 2, s[20:21]
	global_store_dwordx4 v[74:75], v[62:65], off
	v_pk_mul_f32 v[76:77], v[54:55], s[82:83] op_sel_hi:[1,0]
	v_cvt_f16_f32_e32 v54, v54
	v_lshl_add_u64 v[62:63], v[130:131], 0, v[152:153]
	v_exp_f32_e32 v76, v76
	v_exp_f32_e32 v77, v77
	v_pk_add_f32 v[34:35], v[34:35], 1.0 op_sel_hi:[1,0]
	v_pk_add_f32 v[36:37], v[36:37], v[68:69]
	v_rcp_f32_e32 v34, v34
	v_pk_add_f32 v[76:77], v[76:77], 1.0 op_sel_hi:[1,0] neg_lo:[1,0] neg_hi:[1,0]
; __device__ __forceinline__ unsigned pack_f16(float lo, float hi) { const _Float16 a = (_Float16)lo, b = (_Float16)hi; return (unsigned)__builtin_bit_cast(unsigned short, a) | ((unsigned)__builtin_bit_cast(unsigned short, b) << 16); }
;     __device__ __forceinline__ void operator()(const f32x4 (&acc)[2][2][4][2], const Unit& u, int wr, int wc, int fr, int fq) const {
;     ...
;                     for (int j2 = 0; j2 < 2; ++j2) { const int j = 2 * j2;
;                         const f32x2v rp = (f32x2v){acc[ai][0][m][hf][j], acc[ai][0][m][hf][j + 1]} + (f32x2v){bav[j], bav[j + 1]}, ip = (f32x2v){acc[ai][1][m][hf][j], acc[ai][1][m][hf][j + 1]} + (f32x2v){biv[j], biv[j + 1]};
;                         const f32x2v er = rp * (-1.4426950408889634f), ei = ip * (-1.4426950408889634f);
;                         f32x2v tr, ti; tr.x = __builtin_amdgcn_exp2f(er.x); tr.y = __builtin_amdgcn_exp2f(er.y); ti.x = __builtin_amdgcn_exp2f(ei.x); ti.y = __builtin_amdgcn_exp2f(ei.y);
;                         const f32x2v dr = tr + 1.0f, di = ti + 1.0f; f32x2v r, ig; r.x = __builtin_amdgcn_rcpf(dr.x); r.y = __builtin_amdgcn_rcpf(dr.y); ig.x = __builtin_amdgcn_rcpf(di.x); ig.y = __builtin_amdgcn_rcpf(di.y);
;                         const f32x2v la = r * (f32x2v){-sp[j], -sp[j + 1]}, e2 = la * 2.8853900817779268f;
;                         f32x2v a2; a2.x = __builtin_amdgcn_exp2f(e2.x); a2.y = __builtin_amdgcn_exp2f(e2.y);
;                         const f32x2v om = __builtin_elementwise_max(1.0f - a2, (f32x2v){0.f, 0.f}); f32x2v mult; mult.x = __builtin_amdgcn_sqrtf(om.x); mult.y = __builtin_amdgcn_sqrtf(om.y);
;                         const f32x2v bt = (mult * ig) * (f32x2v){xr[j], xr[j + 1]};
;                         w[j] = pack_f16(la.x, bt.x); w[j + 1] = pack_f16(la.y, bt.y); }
;                     *(u32x4*)(AB + off) = w;
	v_rcp_f32_e32 v35, v35
	v_max_f32_e32 v77, 0, v77
	v_max_f32_e32 v76, 0, v76
	v_sqrt_f32_e32 v76, v76
	v_sqrt_f32_e32 v77, v77
	v_pk_mul_f32 v[36:37], v[36:37], s[88:89] op_sel_hi:[1,0]
	v_pk_add_f32 v[30:31], v[30:31], v[70:71]
	v_exp_f32_e32 v36, v36
	v_pk_mul_f32 v[50:51], v[50:51], v[76:77]
	v_exp_f32_e32 v37, v37
	v_pk_mul_f32 v[30:31], v[30:31], s[88:89] op_sel_hi:[1,0]
	v_pk_add_f32 v[26:27], v[26:27], v[66:67]
	v_exp_f32_e32 v30, v30
	v_pk_add_f32 v[36:37], v[36:37], 1.0 op_sel_hi:[1,0]
	v_exp_f32_e32 v31, v31
	v_rcp_f32_e32 v36, v36
	v_rcp_f32_e32 v37, v37
	v_pk_mul_f32 v[26:27], v[26:27], s[88:89] op_sel_hi:[1,0]
	v_pk_add_f32 v[30:31], v[30:31], 1.0 op_sel_hi:[1,0]
	v_exp_f32_e32 v26, v26
	v_rcp_f32_e32 v30, v30
	v_rcp_f32_e32 v31, v31
	v_exp_f32_e32 v27, v27
	v_pk_add_f32 v[32:33], v[32:33], v[72:73]
	v_pk_add_f32 v[28:29], v[28:29], v[68:69]
	v_pk_mul_f32 v[30:31], v[30:31], v[58:59]
	v_pk_add_f32 v[26:27], v[26:27], 1.0 op_sel_hi:[1,0]
	v_pk_mul_f32 v[28:29], v[28:29], s[88:89] op_sel_hi:[1,0]
	v_rcp_f32_e32 v26, v26
	v_rcp_f32_e32 v27, v27
	v_exp_f32_e32 v28, v28
	v_exp_f32_e32 v29, v29
	v_pk_add_f32 v[22:23], v[22:23], v[70:71]
	v_pk_add_f32 v[18:19], v[18:19], v[66:67]
	v_pk_mul_f32 v[22:23], v[22:23], s[88:89] op_sel_hi:[1,0]
	v_pk_add_f32 v[28:29], v[28:29], 1.0 op_sel_hi:[1,0]
	v_exp_f32_e32 v22, v22
	v_rcp_f32_e32 v28, v28
	v_rcp_f32_e32 v29, v29
	v_exp_f32_e32 v23, v23
	v_pk_mul_f32 v[18:19], v[18:19], s[88:89] op_sel_hi:[1,0]
	v_pk_add_f32 v[24:25], v[24:25], v[72:73]
	v_exp_f32_e32 v18, v18
	v_pk_add_f32 v[22:23], v[22:23], 1.0 op_sel_hi:[1,0]
	v_exp_f32_e32 v19, v19
	v_rcp_f32_e32 v22, v22
	v_rcp_f32_e32 v23, v23
	v_pk_add_f32 v[20:21], v[20:21], v[68:69]
	v_pk_add_f32 v[18:19], v[18:19], 1.0 op_sel_hi:[1,0]
	v_pk_mul_f32 v[20:21], v[20:21], s[88:89] op_sel_hi:[1,0]
	v_pk_mul_f32 v[22:23], v[22:23], v[58:59]
	v_rcp_f32_e32 v18, v18
	v_rcp_f32_e32 v19, v19
	v_exp_f32_e32 v20, v20
	v_exp_f32_e32 v21, v21
	v_pk_add_f32 v[14:15], v[14:15], v[70:71]
	v_pk_add_f32 v[10:11], v[10:11], v[66:67]
	v_pk_mul_f32 v[14:15], v[14:15], s[88:89] op_sel_hi:[1,0]
	v_pk_add_f32 v[20:21], v[20:21], 1.0 op_sel_hi:[1,0]
	v_exp_f32_e32 v14, v14
	v_rcp_f32_e32 v20, v20
	v_rcp_f32_e32 v21, v21
	v_exp_f32_e32 v15, v15
	v_pk_mul_f32 v[10:11], v[10:11], s[88:89] op_sel_hi:[1,0]
	v_pk_add_f32 v[16:17], v[16:17], v[72:73]
	v_exp_f32_e32 v10, v10
	v_pk_add_f32 v[14:15], v[14:15], 1.0 op_sel_hi:[1,0]
	v_exp_f32_e32 v11, v11
	v_rcp_f32_e32 v14, v14
	v_rcp_f32_e32 v15, v15
	v_pk_add_f32 v[12:13], v[12:13], v[68:69]
	v_pk_add_f32 v[10:11], v[10:11], 1.0 op_sel_hi:[1,0]
	v_pk_mul_f32 v[12:13], v[12:13], s[88:89] op_sel_hi:[1,0]
	s_waitcnt lgkmcnt(0)
	v_lshlrev_b32_e32 v74, 16, v224
	v_and_b32_e32 v75, 0xffff0000, v224
	v_pk_mul_f32 v[50:51], v[50:51], v[74:75]
	v_lshlrev_b32_e32 v64, 16, v225
	v_cvt_f16_f32_sdwa v50, v50 dst_sel:WORD_1 dst_unused:UNUSED_PAD src0_sel:DWORD
	v_cvt_f16_f32_sdwa v51, v51 dst_sel:WORD_1 dst_unused:UNUSED_PAD src0_sel:DWORD
	v_and_b32_e32 v65, 0xffff0000, v225
	v_pk_mul_f32 v[14:15], v[14:15], v[58:59]
	v_or_b32_e32 v50, v50, v54
	v_cvt_f16_f32_e32 v54, v55
	v_rcp_f32_e32 v10, v10
	v_rcp_f32_e32 v11, v11
	v_exp_f32_e32 v12, v12
	v_or_b32_e32 v51, v51, v54
	v_pk_mul_f32 v[54:55], v[56:57], s[88:89] op_sel_hi:[1,0]
	v_exp_f32_e32 v13, v13
	v_exp_f32_e32 v54, v54
	v_exp_f32_e32 v55, v55
	v_pk_add_f32 v[6:7], v[6:7], v[70:71]
	v_pk_add_f32 v[12:13], v[12:13], 1.0 op_sel_hi:[1,0]
	v_pk_mul_f32 v[6:7], v[6:7], s[88:89] op_sel_hi:[1,0]
	v_pk_add_f32 v[54:55], v[54:55], 1.0 op_sel_hi:[1,0]
	v_rcp_f32_e32 v12, v12
	v_rcp_f32_e32 v54, v54
	v_rcp_f32_e32 v55, v55
	v_rcp_f32_e32 v13, v13
	v_exp_f32_e32 v6, v6
	v_exp_f32_e32 v7, v7
	v_pk_mul_f32 v[54:55], v[54:55], v[60:61]
	v_pk_add_f32 v[2:3], v[2:3], v[66:67]
	v_pk_mul_f32 v[56:57], v[54:55], s[82:83] op_sel_hi:[1,0]
	v_cvt_f16_f32_e32 v54, v54
	v_exp_f32_e32 v56, v56
	v_exp_f32_e32 v57, v57
	v_pk_add_f32 v[6:7], v[6:7], 1.0 op_sel_hi:[1,0]
	v_pk_mul_f32 v[2:3], v[2:3], s[88:89] op_sel_hi:[1,0]
	v_rcp_f32_e32 v6, v6
	v_pk_add_f32 v[56:57], v[56:57], 1.0 op_sel_hi:[1,0] neg_lo:[1,0] neg_hi:[1,0]
	v_rcp_f32_e32 v7, v7
	v_max_f32_e32 v57, 0, v57
	v_max_f32_e32 v56, 0, v56
	v_sqrt_f32_e32 v56, v56
	v_sqrt_f32_e32 v57, v57
	v_pk_mul_f32 v[6:7], v[6:7], v[58:59]
	v_exp_f32_e32 v2, v2
	v_exp_f32_e32 v3, v3
	v_pk_mul_f32 v[52:53], v[52:53], v[56:57]
	v_pk_mul_f32 v[56:57], v[46:47], s[82:83] op_sel_hi:[1,0]
	v_pk_mul_f32 v[52:53], v[52:53], v[64:65]
	v_exp_f32_e32 v56, v56
	v_cvt_f16_f32_sdwa v52, v52 dst_sel:WORD_1 dst_unused:UNUSED_PAD src0_sel:DWORD
	v_cvt_f16_f32_sdwa v53, v53 dst_sel:WORD_1 dst_unused:UNUSED_PAD src0_sel:DWORD
	v_exp_f32_e32 v57, v57
	v_cvt_f16_f32_e32 v46, v46
	v_or_b32_e32 v52, v52, v54
	v_cvt_f16_f32_e32 v54, v55
	v_pk_add_f32 v[56:57], v[56:57], 1.0 op_sel_hi:[1,0] neg_lo:[1,0] neg_hi:[1,0]
	v_pk_add_f32 v[2:3], v[2:3], 1.0 op_sel_hi:[1,0]
	v_max_f32_e32 v57, 0, v57
	v_or_b32_e32 v53, v53, v54
	v_lshl_add_u64 v[54:55], v[62:63], 2, s[20:21]
	global_store_dwordx4 v[54:55], v[50:53], off
	v_max_f32_e32 v56, 0, v56
	v_sqrt_f32_e32 v56, v56
	v_lshl_add_u64 v[50:51], v[122:123], 0, v[152:153]
	v_sqrt_f32_e32 v57, v57
	v_rcp_f32_e32 v2, v2
	v_rcp_f32_e32 v3, v3
	v_pk_add_f32 v[8:9], v[8:9], v[72:73]
	v_pk_mul_f32 v[42:43], v[42:43], v[56:57]
	v_pk_add_f32 v[4:5], v[4:5], v[68:69]
	s_movk_i32 s0, 0x1000
	v_pk_mul_f32 v[4:5], v[4:5], s[88:89] op_sel_hi:[1,0]
	s_mov_b64 s[6:7], -1
	v_exp_f32_e32 v4, v4
	v_exp_f32_e32 v5, v5
	s_waitcnt lgkmcnt(0)
; __device__ __forceinline__ unsigned pack_f16(float lo, float hi) { const _Float16 a = (_Float16)lo, b = (_Float16)hi; return (unsigned)__builtin_bit_cast(unsigned short, a) | ((unsigned)__builtin_bit_cast(unsigned short, b) << 16); }
;     __device__ __forceinline__ void operator()(const f32x4 (&acc)[2][2][4][2], const Unit& u, int wr, int wc, int fr, int fq) const {
;     ...
;                     for (int j2 = 0; j2 < 2; ++j2) { const int j = 2 * j2;
;                         const f32x2v rp = (f32x2v){acc[ai][0][m][hf][j], acc[ai][0][m][hf][j + 1]} + (f32x2v){bav[j], bav[j + 1]}, ip = (f32x2v){acc[ai][1][m][hf][j], acc[ai][1][m][hf][j + 1]} + (f32x2v){biv[j], biv[j + 1]};
;                         const f32x2v er = rp * (-1.4426950408889634f), ei = ip * (-1.4426950408889634f);
;                         f32x2v tr, ti; tr.x = __builtin_amdgcn_exp2f(er.x); tr.y = __builtin_amdgcn_exp2f(er.y); ti.x = __builtin_amdgcn_exp2f(ei.x); ti.y = __builtin_amdgcn_exp2f(ei.y);
;                         const f32x2v dr = tr + 1.0f, di = ti + 1.0f; f32x2v r, ig; r.x = __builtin_amdgcn_rcpf(dr.x); r.y = __builtin_amdgcn_rcpf(dr.y); ig.x = __builtin_amdgcn_rcpf(di.x); ig.y = __builtin_amdgcn_rcpf(di.y);
;                         const f32x2v la = r * (f32x2v){-sp[j], -sp[j + 1]}, e2 = la * 2.8853900817779268f;
;                         f32x2v a2; a2.x = __builtin_amdgcn_exp2f(e2.x); a2.y = __builtin_amdgcn_exp2f(e2.y);
;                         const f32x2v om = __builtin_elementwise_max(1.0f - a2, (f32x2v){0.f, 0.f}); f32x2v mult; mult.x = __builtin_amdgcn_sqrtf(om.x); mult.y = __builtin_amdgcn_sqrtf(om.y);
;                         const f32x2v bt = (mult * ig) * (f32x2v){xr[j], xr[j + 1]};
;                         w[j] = pack_f16(la.x, bt.x); w[j + 1] = pack_f16(la.y, bt.y); }
;                     *(u32x4*)(AB + off) = w;
	v_lshlrev_b32_e32 v54, 16, v226
	v_and_b32_e32 v55, 0xffff0000, v226
	v_pk_mul_f32 v[42:43], v[42:43], v[54:55]
	v_lshlrev_b32_e32 v52, 16, v227
	v_cvt_f16_f32_sdwa v42, v42 dst_sel:WORD_1 dst_unused:UNUSED_PAD src0_sel:DWORD
	v_cvt_f16_f32_sdwa v43, v43 dst_sel:WORD_1 dst_unused:UNUSED_PAD src0_sel:DWORD
	v_and_b32_e32 v53, 0xffff0000, v227
	v_pk_add_f32 v[4:5], v[4:5], 1.0 op_sel_hi:[1,0]
	v_or_b32_e32 v42, v42, v46
	v_cvt_f16_f32_e32 v46, v47
	v_rcp_f32_e32 v4, v4
	v_rcp_f32_e32 v5, v5
	v_or_b32_e32 v43, v43, v46
	v_pk_mul_f32 v[46:47], v[48:49], s[88:89] op_sel_hi:[1,0]
	s_nop 0
	v_exp_f32_e32 v46, v46
	v_exp_f32_e32 v47, v47
	s_nop 0
	v_pk_add_f32 v[46:47], v[46:47], 1.0 op_sel_hi:[1,0]
	s_nop 0
	v_rcp_f32_e32 v46, v46
	v_rcp_f32_e32 v47, v47
	s_nop 0
	v_pk_mul_f32 v[46:47], v[46:47], v[60:61]
	s_nop 0
	v_pk_mul_f32 v[48:49], v[46:47], s[82:83] op_sel_hi:[1,0]
	v_cvt_f16_f32_e32 v46, v46
	v_exp_f32_e32 v48, v48
	v_exp_f32_e32 v49, v49
	s_nop 0
	v_pk_add_f32 v[48:49], v[48:49], 1.0 op_sel_hi:[1,0] neg_lo:[1,0] neg_hi:[1,0]
	s_nop 0
	v_max_f32_e32 v49, 0, v49
	v_max_f32_e32 v48, 0, v48
	v_sqrt_f32_e32 v48, v48
	v_sqrt_f32_e32 v49, v49
	s_nop 0
	v_pk_mul_f32 v[44:45], v[44:45], v[48:49]
	s_nop 0
	v_pk_mul_f32 v[44:45], v[44:45], v[52:53]
	v_pk_mul_f32 v[48:49], v[38:39], s[82:83] op_sel_hi:[1,0]
	v_cvt_f16_f32_sdwa v44, v44 dst_sel:WORD_1 dst_unused:UNUSED_PAD src0_sel:DWORD
	v_cvt_f16_f32_sdwa v45, v45 dst_sel:WORD_1 dst_unused:UNUSED_PAD src0_sel:DWORD
	v_exp_f32_e32 v48, v48
	v_exp_f32_e32 v49, v49
	v_or_b32_e32 v44, v44, v46
	v_cvt_f16_f32_e32 v46, v47
	v_cvt_f16_f32_e32 v38, v38
	v_pk_add_f32 v[48:49], v[48:49], 1.0 op_sel_hi:[1,0] neg_lo:[1,0] neg_hi:[1,0]
	v_or_b32_e32 v45, v45, v46
	v_lshl_add_u64 v[46:47], v[50:51], 2, s[20:21]
	global_store_dwordx4 v[46:47], v[42:45], off
	v_max_f32_e32 v49, 0, v49
	v_max_f32_e32 v48, 0, v48
	v_lshl_add_u64 v[42:43], v[114:115], 0, v[152:153]
	v_sqrt_f32_e32 v48, v48
	v_sqrt_f32_e32 v49, v49
	s_waitcnt lgkmcnt(0)
	v_lshlrev_b32_e32 v46, 16, v228
	v_and_b32_e32 v47, 0xffff0000, v228
	v_pk_mul_f32 v[34:35], v[34:35], v[48:49]
	v_lshlrev_b32_e32 v44, 16, v229
	v_pk_mul_f32 v[34:35], v[34:35], v[46:47]
	v_and_b32_e32 v45, 0xffff0000, v229
	v_cvt_f16_f32_sdwa v34, v34 dst_sel:WORD_1 dst_unused:UNUSED_PAD src0_sel:DWORD
	v_cvt_f16_f32_sdwa v35, v35 dst_sel:WORD_1 dst_unused:UNUSED_PAD src0_sel:DWORD
	v_or_b32_e32 v34, v34, v38
	v_cvt_f16_f32_e32 v38, v39
	v_or_b32_e32 v35, v35, v38
	v_pk_mul_f32 v[38:39], v[40:41], s[88:89] op_sel_hi:[1,0]
	s_nop 0
	v_exp_f32_e32 v38, v38
	v_exp_f32_e32 v39, v39
	s_nop 0
	v_pk_add_f32 v[38:39], v[38:39], 1.0 op_sel_hi:[1,0]
	s_nop 0
	v_rcp_f32_e32 v38, v38
	v_rcp_f32_e32 v39, v39
	s_nop 0
	v_pk_mul_f32 v[38:39], v[38:39], v[60:61]
	s_nop 0
	v_pk_mul_f32 v[40:41], v[38:39], s[82:83] op_sel_hi:[1,0]
	v_cvt_f16_f32_e32 v38, v38
	v_exp_f32_e32 v40, v40
	v_exp_f32_e32 v41, v41
	s_nop 0
	v_pk_add_f32 v[40:41], v[40:41], 1.0 op_sel_hi:[1,0] neg_lo:[1,0] neg_hi:[1,0]
	s_nop 0
	v_max_f32_e32 v41, 0, v41
	v_max_f32_e32 v40, 0, v40
	v_sqrt_f32_e32 v40, v40
	v_sqrt_f32_e32 v41, v41
	s_nop 0
	v_pk_mul_f32 v[36:37], v[36:37], v[40:41]
	s_nop 0
	v_pk_mul_f32 v[36:37], v[36:37], v[44:45]
	v_pk_mul_f32 v[40:41], v[30:31], s[82:83] op_sel_hi:[1,0]
	v_cvt_f16_f32_sdwa v36, v36 dst_sel:WORD_1 dst_unused:UNUSED_PAD src0_sel:DWORD
	v_cvt_f16_f32_sdwa v37, v37 dst_sel:WORD_1 dst_unused:UNUSED_PAD src0_sel:DWORD
	v_exp_f32_e32 v40, v40
	v_exp_f32_e32 v41, v41
	v_or_b32_e32 v36, v36, v38
	v_cvt_f16_f32_e32 v38, v39
	v_cvt_f16_f32_e32 v30, v30
	v_pk_add_f32 v[40:41], v[40:41], 1.0 op_sel_hi:[1,0] neg_lo:[1,0] neg_hi:[1,0]
	v_or_b32_e32 v37, v37, v38
	v_lshl_add_u64 v[38:39], v[42:43], 2, s[20:21]
	global_store_dwordx4 v[38:39], v[34:37], off
	v_max_f32_e32 v41, 0, v41
	v_max_f32_e32 v40, 0, v40
	v_lshl_add_u64 v[34:35], v[106:107], 0, v[152:153]
	v_sqrt_f32_e32 v40, v40
	v_sqrt_f32_e32 v41, v41
	s_waitcnt lgkmcnt(0)
	v_lshlrev_b32_e32 v38, 16, v230
	v_and_b32_e32 v39, 0xffff0000, v230
	v_pk_mul_f32 v[26:27], v[26:27], v[40:41]
	v_lshlrev_b32_e32 v36, 16, v231
	v_pk_mul_f32 v[26:27], v[26:27], v[38:39]
	v_and_b32_e32 v37, 0xffff0000, v231
	v_cvt_f16_f32_sdwa v26, v26 dst_sel:WORD_1 dst_unused:UNUSED_PAD src0_sel:DWORD
	v_cvt_f16_f32_sdwa v27, v27 dst_sel:WORD_1 dst_unused:UNUSED_PAD src0_sel:DWORD
	v_or_b32_e32 v26, v26, v30
	v_cvt_f16_f32_e32 v30, v31
	v_or_b32_e32 v27, v27, v30
	v_pk_mul_f32 v[30:31], v[32:33], s[88:89] op_sel_hi:[1,0]
	s_nop 0
	v_exp_f32_e32 v30, v30
	v_exp_f32_e32 v31, v31
	s_nop 0
	v_pk_add_f32 v[30:31], v[30:31], 1.0 op_sel_hi:[1,0]
	s_nop 0
	v_rcp_f32_e32 v30, v30
	v_rcp_f32_e32 v31, v31
	s_nop 0
	v_pk_mul_f32 v[30:31], v[30:31], v[60:61]
	s_nop 0
	v_pk_mul_f32 v[32:33], v[30:31], s[82:83] op_sel_hi:[1,0]
	v_cvt_f16_f32_e32 v30, v30
	v_exp_f32_e32 v32, v32
	v_exp_f32_e32 v33, v33
	s_nop 0
	v_pk_add_f32 v[32:33], v[32:33], 1.0 op_sel_hi:[1,0] neg_lo:[1,0] neg_hi:[1,0]
	s_nop 0
	v_max_f32_e32 v33, 0, v33
	v_max_f32_e32 v32, 0, v32
	v_sqrt_f32_e32 v32, v32
	v_sqrt_f32_e32 v33, v33
	s_nop 0
	v_pk_mul_f32 v[28:29], v[28:29], v[32:33]
	s_nop 0
	v_pk_mul_f32 v[28:29], v[28:29], v[36:37]
	v_pk_mul_f32 v[32:33], v[22:23], s[82:83] op_sel_hi:[1,0]
	v_cvt_f16_f32_sdwa v28, v28 dst_sel:WORD_1 dst_unused:UNUSED_PAD src0_sel:DWORD
	v_cvt_f16_f32_sdwa v29, v29 dst_sel:WORD_1 dst_unused:UNUSED_PAD src0_sel:DWORD
	v_exp_f32_e32 v32, v32
	v_exp_f32_e32 v33, v33
	v_or_b32_e32 v28, v28, v30
	v_cvt_f16_f32_e32 v30, v31
	v_cvt_f16_f32_e32 v22, v22
	v_pk_add_f32 v[32:33], v[32:33], 1.0 op_sel_hi:[1,0] neg_lo:[1,0] neg_hi:[1,0]
	v_or_b32_e32 v29, v29, v30
	v_lshl_add_u64 v[30:31], v[34:35], 2, s[20:21]
	global_store_dwordx4 v[30:31], v[26:29], off
	v_max_f32_e32 v33, 0, v33
	v_max_f32_e32 v32, 0, v32
	v_lshl_add_u64 v[26:27], v[98:99], 0, v[152:153]
	v_sqrt_f32_e32 v32, v32
	v_sqrt_f32_e32 v33, v33
	s_waitcnt lgkmcnt(0)
; __device__ __forceinline__ unsigned pack_f16(float lo, float hi) { const _Float16 a = (_Float16)lo, b = (_Float16)hi; return (unsigned)__builtin_bit_cast(unsigned short, a) | ((unsigned)__builtin_bit_cast(unsigned short, b) << 16); }
;     __device__ __forceinline__ void operator()(const f32x4 (&acc)[2][2][4][2], const Unit& u, int wr, int wc, int fr, int fq) const {
;     ...
;                     for (int j2 = 0; j2 < 2; ++j2) { const int j = 2 * j2;
;                         const f32x2v rp = (f32x2v){acc[ai][0][m][hf][j], acc[ai][0][m][hf][j + 1]} + (f32x2v){bav[j], bav[j + 1]}, ip = (f32x2v){acc[ai][1][m][hf][j], acc[ai][1][m][hf][j + 1]} + (f32x2v){biv[j], biv[j + 1]};
;                         const f32x2v er = rp * (-1.4426950408889634f), ei = ip * (-1.4426950408889634f);
;                         f32x2v tr, ti; tr.x = __builtin_amdgcn_exp2f(er.x); tr.y = __builtin_amdgcn_exp2f(er.y); ti.x = __builtin_amdgcn_exp2f(ei.x); ti.y = __builtin_amdgcn_exp2f(ei.y);
;                         const f32x2v dr = tr + 1.0f, di = ti + 1.0f; f32x2v r, ig; r.x = __builtin_amdgcn_rcpf(dr.x); r.y = __builtin_amdgcn_rcpf(dr.y); ig.x = __builtin_amdgcn_rcpf(di.x); ig.y = __builtin_amdgcn_rcpf(di.y);
;                         const f32x2v la = r * (f32x2v){-sp[j], -sp[j + 1]}, e2 = la * 2.8853900817779268f;
;                         f32x2v a2; a2.x = __builtin_amdgcn_exp2f(e2.x); a2.y = __builtin_amdgcn_exp2f(e2.y);
;                         const f32x2v om = __builtin_elementwise_max(1.0f - a2, (f32x2v){0.f, 0.f}); f32x2v mult; mult.x = __builtin_amdgcn_sqrtf(om.x); mult.y = __builtin_amdgcn_sqrtf(om.y);
;                         const f32x2v bt = (mult * ig) * (f32x2v){xr[j], xr[j + 1]};
;                         w[j] = pack_f16(la.x, bt.x); w[j + 1] = pack_f16(la.y, bt.y); }
;                     *(u32x4*)(AB + off) = w;
;                     asm volatile("" ::: "memory");
;                 }
;         }
;         asm volatile("s_waitcnt vmcnt(0)" ::: "memory"); __builtin_amdgcn_s_barrier(); asm volatile("" ::: "memory");
	v_lshlrev_b32_e32 v30, 16, v232
	v_and_b32_e32 v31, 0xffff0000, v232
	v_pk_mul_f32 v[18:19], v[18:19], v[32:33]
	v_lshlrev_b32_e32 v28, 16, v233
	v_pk_mul_f32 v[18:19], v[18:19], v[30:31]
	v_and_b32_e32 v29, 0xffff0000, v233
	v_cvt_f16_f32_sdwa v18, v18 dst_sel:WORD_1 dst_unused:UNUSED_PAD src0_sel:DWORD
	v_cvt_f16_f32_sdwa v19, v19 dst_sel:WORD_1 dst_unused:UNUSED_PAD src0_sel:DWORD
	v_or_b32_e32 v18, v18, v22
	v_cvt_f16_f32_e32 v22, v23
	v_or_b32_e32 v19, v19, v22
	v_pk_mul_f32 v[22:23], v[24:25], s[88:89] op_sel_hi:[1,0]
	s_nop 0
	v_exp_f32_e32 v22, v22
	v_exp_f32_e32 v23, v23
	s_nop 0
	v_pk_add_f32 v[22:23], v[22:23], 1.0 op_sel_hi:[1,0]
	s_nop 0
	v_rcp_f32_e32 v22, v22
	v_rcp_f32_e32 v23, v23
	s_nop 0
	v_pk_mul_f32 v[22:23], v[22:23], v[60:61]
	s_nop 0
	v_pk_mul_f32 v[24:25], v[22:23], s[82:83] op_sel_hi:[1,0]
	v_cvt_f16_f32_e32 v22, v22
	v_exp_f32_e32 v24, v24
	v_exp_f32_e32 v25, v25
	s_nop 0
	v_pk_add_f32 v[24:25], v[24:25], 1.0 op_sel_hi:[1,0] neg_lo:[1,0] neg_hi:[1,0]
	s_nop 0
	v_max_f32_e32 v25, 0, v25
	v_max_f32_e32 v24, 0, v24
	v_sqrt_f32_e32 v24, v24
	v_sqrt_f32_e32 v25, v25
	s_nop 0
	v_pk_mul_f32 v[20:21], v[20:21], v[24:25]
	s_nop 0
	v_pk_mul_f32 v[20:21], v[20:21], v[28:29]
	v_pk_mul_f32 v[24:25], v[14:15], s[82:83] op_sel_hi:[1,0]
	v_cvt_f16_f32_sdwa v20, v20 dst_sel:WORD_1 dst_unused:UNUSED_PAD src0_sel:DWORD
	v_cvt_f16_f32_sdwa v21, v21 dst_sel:WORD_1 dst_unused:UNUSED_PAD src0_sel:DWORD
	v_exp_f32_e32 v24, v24
	v_exp_f32_e32 v25, v25
	v_or_b32_e32 v20, v20, v22
	v_cvt_f16_f32_e32 v22, v23
	v_cvt_f16_f32_e32 v14, v14
	v_pk_add_f32 v[24:25], v[24:25], 1.0 op_sel_hi:[1,0] neg_lo:[1,0] neg_hi:[1,0]
	v_or_b32_e32 v21, v21, v22
	v_lshl_add_u64 v[22:23], v[26:27], 2, s[20:21]
	global_store_dwordx4 v[22:23], v[18:21], off
	v_max_f32_e32 v25, 0, v25
	v_max_f32_e32 v24, 0, v24
	v_lshl_add_u64 v[18:19], v[90:91], 0, v[152:153]
	v_sqrt_f32_e32 v24, v24
	v_sqrt_f32_e32 v25, v25
	s_waitcnt lgkmcnt(0)
	v_lshlrev_b32_e32 v22, 16, v234
	v_and_b32_e32 v23, 0xffff0000, v234
	v_pk_mul_f32 v[10:11], v[10:11], v[24:25]
	v_lshlrev_b32_e32 v20, 16, v235
	v_pk_mul_f32 v[10:11], v[10:11], v[22:23]
	v_and_b32_e32 v21, 0xffff0000, v235
	v_cvt_f16_f32_sdwa v10, v10 dst_sel:WORD_1 dst_unused:UNUSED_PAD src0_sel:DWORD
	v_cvt_f16_f32_sdwa v11, v11 dst_sel:WORD_1 dst_unused:UNUSED_PAD src0_sel:DWORD
	v_or_b32_e32 v10, v10, v14
	v_cvt_f16_f32_e32 v14, v15
	v_or_b32_e32 v11, v11, v14
	v_pk_mul_f32 v[14:15], v[16:17], s[88:89] op_sel_hi:[1,0]
	s_nop 0
	v_exp_f32_e32 v14, v14
	v_exp_f32_e32 v15, v15
	s_nop 0
	v_pk_add_f32 v[14:15], v[14:15], 1.0 op_sel_hi:[1,0]
	s_nop 0
	v_rcp_f32_e32 v14, v14
	v_rcp_f32_e32 v15, v15
	s_nop 0
	v_pk_mul_f32 v[14:15], v[14:15], v[60:61]
	s_nop 0
	v_pk_mul_f32 v[16:17], v[14:15], s[82:83] op_sel_hi:[1,0]
	v_cvt_f16_f32_e32 v14, v14
	v_exp_f32_e32 v16, v16
	v_exp_f32_e32 v17, v17
	s_nop 0
	v_pk_add_f32 v[16:17], v[16:17], 1.0 op_sel_hi:[1,0] neg_lo:[1,0] neg_hi:[1,0]
	s_nop 0
	v_max_f32_e32 v17, 0, v17
	v_max_f32_e32 v16, 0, v16
	v_sqrt_f32_e32 v16, v16
	v_sqrt_f32_e32 v17, v17
	s_nop 0
	v_pk_mul_f32 v[12:13], v[12:13], v[16:17]
	s_nop 0
	v_pk_mul_f32 v[12:13], v[12:13], v[20:21]
	v_pk_mul_f32 v[16:17], v[6:7], s[82:83] op_sel_hi:[1,0]
	v_cvt_f16_f32_sdwa v12, v12 dst_sel:WORD_1 dst_unused:UNUSED_PAD src0_sel:DWORD
	v_cvt_f16_f32_sdwa v13, v13 dst_sel:WORD_1 dst_unused:UNUSED_PAD src0_sel:DWORD
	v_exp_f32_e32 v16, v16
	v_exp_f32_e32 v17, v17
	v_or_b32_e32 v12, v12, v14
	v_cvt_f16_f32_e32 v14, v15
	v_cvt_f16_f32_e32 v6, v6
	v_pk_add_f32 v[16:17], v[16:17], 1.0 op_sel_hi:[1,0] neg_lo:[1,0] neg_hi:[1,0]
	v_or_b32_e32 v13, v13, v14
	v_lshl_add_u64 v[14:15], v[18:19], 2, s[20:21]
	global_store_dwordx4 v[14:15], v[10:13], off
	v_max_f32_e32 v17, 0, v17
	v_max_f32_e32 v16, 0, v16
	v_lshl_add_u64 v[10:11], v[78:79], 0, v[152:153]
	v_sqrt_f32_e32 v16, v16
	v_sqrt_f32_e32 v17, v17
	s_waitcnt lgkmcnt(0)
	v_lshlrev_b32_e32 v14, 16, v236
	v_and_b32_e32 v15, 0xffff0000, v236
	v_pk_mul_f32 v[2:3], v[2:3], v[16:17]
	v_lshlrev_b32_e32 v12, 16, v237
	v_pk_mul_f32 v[2:3], v[2:3], v[14:15]
	v_and_b32_e32 v13, 0xffff0000, v237
	v_cvt_f16_f32_sdwa v2, v2 dst_sel:WORD_1 dst_unused:UNUSED_PAD src0_sel:DWORD
	v_cvt_f16_f32_sdwa v3, v3 dst_sel:WORD_1 dst_unused:UNUSED_PAD src0_sel:DWORD
	v_or_b32_e32 v2, v2, v6
	v_cvt_f16_f32_e32 v6, v7
	v_or_b32_e32 v3, v3, v6
	v_pk_mul_f32 v[6:7], v[8:9], s[88:89] op_sel_hi:[1,0]
	s_nop 0
	v_exp_f32_e32 v6, v6
	v_exp_f32_e32 v7, v7
	s_nop 0
	v_pk_add_f32 v[6:7], v[6:7], 1.0 op_sel_hi:[1,0]
	s_nop 0
	v_rcp_f32_e32 v6, v6
	v_rcp_f32_e32 v7, v7
	s_nop 0
	v_pk_mul_f32 v[6:7], v[6:7], v[60:61]
	s_nop 0
	v_pk_mul_f32 v[8:9], v[6:7], s[82:83] op_sel_hi:[1,0]
	v_cvt_f16_f32_e32 v6, v6
	v_exp_f32_e32 v8, v8
	v_exp_f32_e32 v9, v9
	s_nop 0
	v_pk_add_f32 v[8:9], v[8:9], 1.0 op_sel_hi:[1,0] neg_lo:[1,0] neg_hi:[1,0]
	s_nop 0
	v_max_f32_e32 v9, 0, v9
	v_max_f32_e32 v8, 0, v8
	v_sqrt_f32_e32 v8, v8
	v_sqrt_f32_e32 v9, v9
	s_nop 0
	v_pk_mul_f32 v[4:5], v[4:5], v[8:9]
	s_nop 0
	v_pk_mul_f32 v[4:5], v[4:5], v[12:13]
	s_nop 0
	v_cvt_f16_f32_sdwa v4, v4 dst_sel:WORD_1 dst_unused:UNUSED_PAD src0_sel:DWORD
	v_cvt_f16_f32_sdwa v5, v5 dst_sel:WORD_1 dst_unused:UNUSED_PAD src0_sel:DWORD
	v_or_b32_e32 v4, v4, v6
	v_cvt_f16_f32_e32 v6, v7
	v_or_b32_e32 v5, v5, v6
	v_lshl_add_u64 v[6:7], v[10:11], 2, s[20:21]
	global_store_dwordx4 v[6:7], v[2:5], off
	s_waitcnt vmcnt(0)
	s_barrier
;     __device__ __forceinline__ void operator()(const f32x4 (&acc)[2][2][4][2], const Unit& u, int wr, int wc, int fr, int fq) const {
;     ...
;         { const int t = (4 * wr + wc) * 64 + fq * 16 + fr, chunk = t >> 7, c = (u.pn >> 1) * 256 + (u.pn & 1) * 128 + (t & 127), r0 = u.pm * BM + chunk * 64;
;           const unsigned* ab = AB + (size_t)r0 * D + c; float h = 0.f, L = 0.f;
; #pragma unroll
;           for (int b4 = 0; b4 < 4; ++b4) { unsigned w[16];
; #pragma unroll
;               for (int i = 0; i < 16; ++i) w[i] = ab[(size_t)(b4 * 16 + i) * D];
	s_nop 0
	v_and_b32_e32 v2, -16, v170
	v_add_u32_e32 v3, s54, v2
	v_and_b32_e32 v2, 0x70, v3
	v_ashrrev_i32_e32 v3, 1, v3
	v_and_b32_e32 v3, 0xffffffc0, v3
	v_add_u32_e32 v4, s39, v3
	v_ashrrev_i32_e32 v5, 31, v4
	v_or3_b32 v2, s38, v2, v171
	v_lshlrev_b64 v[6:7], 12, v[4:5]
	v_lshl_add_u64 v[6:7], s[20:21], 0, v[6:7]
	v_ashrrev_i32_e32 v3, 31, v2
	v_lshl_add_u64 v[6:7], v[2:3], 2, v[6:7]
	v_ashrrev_i32_e32 v4, 6, v4
	s_mov_b32 s98, 0x1000
	s_mov_b32 s99, 0
	v_mov_b64_e32 v[8:9], v[6:7]
	global_load_dword v26, v[8:9], off
	v_lshl_add_u64 v[8:9], v[8:9], 0, s[98:99]
	global_load_dword v27, v[8:9], off
	v_lshl_add_u64 v[8:9], v[8:9], 0, s[98:99]
	global_load_dword v28, v[8:9], off
	v_lshl_add_u64 v[8:9], v[8:9], 0, s[98:99]
	global_load_dword v29, v[8:9], off
	v_lshl_add_u64 v[8:9], v[8:9], 0, s[98:99]
	global_load_dword v30, v[8:9], off
	v_lshl_add_u64 v[8:9], v[8:9], 0, s[98:99]
	global_load_dword v31, v[8:9], off
	v_lshl_add_u64 v[8:9], v[8:9], 0, s[98:99]
	global_load_dword v32, v[8:9], off
	v_lshl_add_u64 v[8:9], v[8:9], 0, s[98:99]
	global_load_dword v33, v[8:9], off
	v_lshl_add_u64 v[8:9], v[8:9], 0, s[98:99]
	global_load_dword v34, v[8:9], off
	v_lshl_add_u64 v[8:9], v[8:9], 0, s[98:99]
	global_load_dword v35, v[8:9], off
	v_lshl_add_u64 v[8:9], v[8:9], 0, s[98:99]
	global_load_dword v36, v[8:9], off
	v_lshl_add_u64 v[8:9], v[8:9], 0, s[98:99]
	global_load_dword v37, v[8:9], off
	v_lshl_add_u64 v[8:9], v[8:9], 0, s[98:99]
	global_load_dword v38, v[8:9], off
	v_lshl_add_u64 v[8:9], v[8:9], 0, s[98:99]
	global_load_dword v39, v[8:9], off
	v_lshl_add_u64 v[8:9], v[8:9], 0, s[98:99]
	global_load_dword v40, v[8:9], off
	v_lshl_add_u64 v[8:9], v[8:9], 0, s[98:99]
	global_load_dword v41, v[8:9], off
	v_lshl_add_u64 v[8:9], v[8:9], 0, s[98:99]
	global_load_dword v42, v[8:9], off
	v_lshl_add_u64 v[8:9], v[8:9], 0, s[98:99]
	global_load_dword v43, v[8:9], off
	v_lshl_add_u64 v[8:9], v[8:9], 0, s[98:99]
	global_load_dword v44, v[8:9], off
	v_lshl_add_u64 v[8:9], v[8:9], 0, s[98:99]
	global_load_dword v45, v[8:9], off
	v_lshl_add_u64 v[8:9], v[8:9], 0, s[98:99]
	global_load_dword v46, v[8:9], off
	v_lshl_add_u64 v[8:9], v[8:9], 0, s[98:99]
	global_load_dword v47, v[8:9], off
	v_lshl_add_u64 v[8:9], v[8:9], 0, s[98:99]
	global_load_dword v48, v[8:9], off
	v_lshl_add_u64 v[8:9], v[8:9], 0, s[98:99]
	global_load_dword v49, v[8:9], off
	v_lshl_add_u64 v[8:9], v[8:9], 0, s[98:99]
	global_load_dword v50, v[8:9], off
	v_lshl_add_u64 v[8:9], v[8:9], 0, s[98:99]
	global_load_dword v51, v[8:9], off
	v_lshl_add_u64 v[8:9], v[8:9], 0, s[98:99]
	global_load_dword v52, v[8:9], off
	v_lshl_add_u64 v[8:9], v[8:9], 0, s[98:99]
	global_load_dword v53, v[8:9], off
	v_lshl_add_u64 v[8:9], v[8:9], 0, s[98:99]
	global_load_dword v54, v[8:9], off
	v_lshl_add_u64 v[8:9], v[8:9], 0, s[98:99]
	global_load_dword v55, v[8:9], off
	v_lshl_add_u64 v[8:9], v[8:9], 0, s[98:99]
	global_load_dword v56, v[8:9], off
	v_lshl_add_u64 v[8:9], v[8:9], 0, s[98:99]
	global_load_dword v57, v[8:9], off
	v_lshl_add_u64 v[8:9], v[8:9], 0, s[98:99]
	global_load_dword v58, v[8:9], off
	v_lshl_add_u64 v[8:9], v[8:9], 0, s[98:99]
	global_load_dword v59, v[8:9], off
	v_lshl_add_u64 v[8:9], v[8:9], 0, s[98:99]
	global_load_dword v60, v[8:9], off
	v_lshl_add_u64 v[8:9], v[8:9], 0, s[98:99]
	global_load_dword v61, v[8:9], off
	v_lshl_add_u64 v[8:9], v[8:9], 0, s[98:99]
	global_load_dword v62, v[8:9], off
	v_lshl_add_u64 v[8:9], v[8:9], 0, s[98:99]
	global_load_dword v63, v[8:9], off
	v_lshl_add_u64 v[8:9], v[8:9], 0, s[98:99]
	global_load_dword v64, v[8:9], off
	v_lshl_add_u64 v[8:9], v[8:9], 0, s[98:99]
	global_load_dword v65, v[8:9], off
	v_lshl_add_u64 v[8:9], v[8:9], 0, s[98:99]
	global_load_dword v66, v[8:9], off
	v_lshl_add_u64 v[8:9], v[8:9], 0, s[98:99]
	global_load_dword v67, v[8:9], off
	v_lshl_add_u64 v[8:9], v[8:9], 0, s[98:99]
	global_load_dword v68, v[8:9], off
	v_lshl_add_u64 v[8:9], v[8:9], 0, s[98:99]
	global_load_dword v69, v[8:9], off
	v_lshl_add_u64 v[8:9], v[8:9], 0, s[98:99]
	global_load_dword v70, v[8:9], off
	v_lshl_add_u64 v[8:9], v[8:9], 0, s[98:99]
	global_load_dword v71, v[8:9], off
	v_lshl_add_u64 v[8:9], v[8:9], 0, s[98:99]
	global_load_dword v72, v[8:9], off
	v_lshl_add_u64 v[8:9], v[8:9], 0, s[98:99]
	global_load_dword v73, v[8:9], off
	v_lshl_add_u64 v[8:9], v[8:9], 0, s[98:99]
	global_load_dword v74, v[8:9], off
	v_lshl_add_u64 v[8:9], v[8:9], 0, s[98:99]
	global_load_dword v75, v[8:9], off
	v_lshl_add_u64 v[8:9], v[8:9], 0, s[98:99]
	global_load_dword v76, v[8:9], off
	v_lshl_add_u64 v[8:9], v[8:9], 0, s[98:99]
	global_load_dword v77, v[8:9], off
	v_lshl_add_u64 v[8:9], v[8:9], 0, s[98:99]
	global_load_dword v78, v[8:9], off
	v_lshl_add_u64 v[8:9], v[8:9], 0, s[98:99]
	global_load_dword v79, v[8:9], off
	v_lshl_add_u64 v[8:9], v[8:9], 0, s[98:99]
	global_load_dword v80, v[8:9], off
	v_lshl_add_u64 v[8:9], v[8:9], 0, s[98:99]
	global_load_dword v81, v[8:9], off
	v_lshl_add_u64 v[8:9], v[8:9], 0, s[98:99]
	global_load_dword v82, v[8:9], off
	v_lshl_add_u64 v[8:9], v[8:9], 0, s[98:99]
	global_load_dword v83, v[8:9], off
	v_lshl_add_u64 v[8:9], v[8:9], 0, s[98:99]
	global_load_dword v84, v[8:9], off
	v_lshl_add_u64 v[8:9], v[8:9], 0, s[98:99]
	global_load_dword v85, v[8:9], off
	v_lshl_add_u64 v[8:9], v[8:9], 0, s[98:99]
	global_load_dword v86, v[8:9], off
	v_lshl_add_u64 v[8:9], v[8:9], 0, s[98:99]
	global_load_dword v87, v[8:9], off
	v_lshl_add_u64 v[8:9], v[8:9], 0, s[98:99]
	global_load_dword v88, v[8:9], off
	v_lshl_add_u64 v[8:9], v[8:9], 0, s[98:99]
	global_load_dword v89, v[8:9], off
	s_waitcnt vmcnt(63)
; __device__ __forceinline__ float f16_lo(unsigned w) { return (float)__builtin_bit_cast(_Float16, (unsigned short)(w & 0xffffu)); }
; __device__ __forceinline__ float f16_hi(unsigned w) { return (float)__builtin_bit_cast(_Float16, (unsigned short)(w >> 16)); }
;     __device__ __forceinline__ void operator()(const f32x4 (&acc)[2][2][4][2], const Unit& u, int wr, int wc, int fr, int fq) const {
;     ...
;           for (int b4 = 0; b4 < 4; ++b4) { unsigned w[16];
; #pragma unroll
;               for (int i = 0; i < 16; ++i) w[i] = ab[(size_t)(b4 * 16 + i) * D];
; #pragma unroll
;               for (int i = 0; i < 16; ++i) { const float la = f16_lo(w[i]); h = __expf(la) * h + f16_hi(w[i]); L += la; } }
	v_cvt_f32_f16_e32 v10, v26
	v_mul_f32_e32 v11, 0x3fb8aa3b, v10
	v_exp_f32_e32 v11, v11
	v_add_f32_e32 v15, 0, v10
	v_fma_mix_f32 v14, v11, 0, v26 op_sel:[0,0,1] op_sel_hi:[0,0,1]
	s_waitcnt vmcnt(62)
	v_cvt_f32_f16_e32 v12, v27
	v_mul_f32_e32 v13, 0x3fb8aa3b, v12
	v_exp_f32_e32 v13, v13
	v_add_f32_e32 v15, v15, v12
	v_fma_mix_f32 v14, v13, v14, v27 op_sel:[0,0,1] op_sel_hi:[0,0,1]
	s_waitcnt vmcnt(61)
	v_cvt_f32_f16_e32 v10, v28
	v_mul_f32_e32 v11, 0x3fb8aa3b, v10
	v_exp_f32_e32 v11, v11
	v_add_f32_e32 v15, v15, v10
	v_fma_mix_f32 v14, v11, v14, v28 op_sel:[0,0,1] op_sel_hi:[0,0,1]
	s_waitcnt vmcnt(60)
	v_cvt_f32_f16_e32 v12, v29
	v_mul_f32_e32 v13, 0x3fb8aa3b, v12
	v_exp_f32_e32 v13, v13
	v_add_f32_e32 v15, v15, v12
	v_fma_mix_f32 v14, v13, v14, v29 op_sel:[0,0,1] op_sel_hi:[0,0,1]
	s_waitcnt vmcnt(59)
	v_cvt_f32_f16_e32 v10, v30
	v_mul_f32_e32 v11, 0x3fb8aa3b, v10
	v_exp_f32_e32 v11, v11
	v_add_f32_e32 v15, v15, v10
	v_fma_mix_f32 v14, v11, v14, v30 op_sel:[0,0,1] op_sel_hi:[0,0,1]
	s_waitcnt vmcnt(58)
	v_cvt_f32_f16_e32 v12, v31
	v_mul_f32_e32 v13, 0x3fb8aa3b, v12
	v_exp_f32_e32 v13, v13
	v_add_f32_e32 v15, v15, v12
	v_fma_mix_f32 v14, v13, v14, v31 op_sel:[0,0,1] op_sel_hi:[0,0,1]
	s_waitcnt vmcnt(57)
	v_cvt_f32_f16_e32 v10, v32
	v_mul_f32_e32 v11, 0x3fb8aa3b, v10
	v_exp_f32_e32 v11, v11
	v_add_f32_e32 v15, v15, v10
	v_fma_mix_f32 v14, v11, v14, v32 op_sel:[0,0,1] op_sel_hi:[0,0,1]
	s_waitcnt vmcnt(56)
	v_cvt_f32_f16_e32 v12, v33
	v_mul_f32_e32 v13, 0x3fb8aa3b, v12
	v_exp_f32_e32 v13, v13
	v_add_f32_e32 v15, v15, v12
	v_fma_mix_f32 v14, v13, v14, v33 op_sel:[0,0,1] op_sel_hi:[0,0,1]
	s_waitcnt vmcnt(55)
	v_cvt_f32_f16_e32 v10, v34
	v_mul_f32_e32 v11, 0x3fb8aa3b, v10
	v_exp_f32_e32 v11, v11
	v_add_f32_e32 v15, v15, v10
	v_fma_mix_f32 v14, v11, v14, v34 op_sel:[0,0,1] op_sel_hi:[0,0,1]
	s_waitcnt vmcnt(54)
	v_cvt_f32_f16_e32 v12, v35
	v_mul_f32_e32 v13, 0x3fb8aa3b, v12
	v_exp_f32_e32 v13, v13
	v_add_f32_e32 v15, v15, v12
	v_fma_mix_f32 v14, v13, v14, v35 op_sel:[0,0,1] op_sel_hi:[0,0,1]
	s_waitcnt vmcnt(53)
	v_cvt_f32_f16_e32 v10, v36
	v_mul_f32_e32 v11, 0x3fb8aa3b, v10
	v_exp_f32_e32 v11, v11
	v_add_f32_e32 v15, v15, v10
	v_fma_mix_f32 v14, v11, v14, v36 op_sel:[0,0,1] op_sel_hi:[0,0,1]
	s_waitcnt vmcnt(52)
	v_cvt_f32_f16_e32 v12, v37
	v_mul_f32_e32 v13, 0x3fb8aa3b, v12
	v_exp_f32_e32 v13, v13
	v_add_f32_e32 v15, v15, v12
	v_fma_mix_f32 v14, v13, v14, v37 op_sel:[0,0,1] op_sel_hi:[0,0,1]
	s_waitcnt vmcnt(51)
	v_cvt_f32_f16_e32 v10, v38
	v_mul_f32_e32 v11, 0x3fb8aa3b, v10
	v_exp_f32_e32 v11, v11
	v_add_f32_e32 v15, v15, v10
	v_fma_mix_f32 v14, v11, v14, v38 op_sel:[0,0,1] op_sel_hi:[0,0,1]
	s_waitcnt vmcnt(50)
	v_cvt_f32_f16_e32 v12, v39
	v_mul_f32_e32 v13, 0x3fb8aa3b, v12
	v_exp_f32_e32 v13, v13
	v_add_f32_e32 v15, v15, v12
	v_fma_mix_f32 v14, v13, v14, v39 op_sel:[0,0,1] op_sel_hi:[0,0,1]
	s_waitcnt vmcnt(49)
	v_cvt_f32_f16_e32 v10, v40
	v_mul_f32_e32 v11, 0x3fb8aa3b, v10
	v_exp_f32_e32 v11, v11
	v_add_f32_e32 v15, v15, v10
	v_fma_mix_f32 v14, v11, v14, v40 op_sel:[0,0,1] op_sel_hi:[0,0,1]
	s_waitcnt vmcnt(48)
	v_cvt_f32_f16_e32 v12, v41
	v_mul_f32_e32 v13, 0x3fb8aa3b, v12
	v_exp_f32_e32 v13, v13
	v_add_f32_e32 v15, v15, v12
	v_fma_mix_f32 v14, v13, v14, v41 op_sel:[0,0,1] op_sel_hi:[0,0,1]
	s_waitcnt vmcnt(47)
	v_cvt_f32_f16_e32 v10, v42
	v_mul_f32_e32 v11, 0x3fb8aa3b, v10
	v_exp_f32_e32 v11, v11
	v_add_f32_e32 v15, v15, v10
	v_fma_mix_f32 v14, v11, v14, v42 op_sel:[0,0,1] op_sel_hi:[0,0,1]
	s_waitcnt vmcnt(46)
	v_cvt_f32_f16_e32 v12, v43
	v_mul_f32_e32 v13, 0x3fb8aa3b, v12
	v_exp_f32_e32 v13, v13
	v_add_f32_e32 v15, v15, v12
	v_fma_mix_f32 v14, v13, v14, v43 op_sel:[0,0,1] op_sel_hi:[0,0,1]
	s_waitcnt vmcnt(45)
	v_cvt_f32_f16_e32 v10, v44
	v_mul_f32_e32 v11, 0x3fb8aa3b, v10
	v_exp_f32_e32 v11, v11
	v_add_f32_e32 v15, v15, v10
	v_fma_mix_f32 v14, v11, v14, v44 op_sel:[0,0,1] op_sel_hi:[0,0,1]
	s_waitcnt vmcnt(44)
	v_cvt_f32_f16_e32 v12, v45
	v_mul_f32_e32 v13, 0x3fb8aa3b, v12
	v_exp_f32_e32 v13, v13
	v_add_f32_e32 v15, v15, v12
	v_fma_mix_f32 v14, v13, v14, v45 op_sel:[0,0,1] op_sel_hi:[0,0,1]
	s_waitcnt vmcnt(43)
	v_cvt_f32_f16_e32 v10, v46
	v_mul_f32_e32 v11, 0x3fb8aa3b, v10
	v_exp_f32_e32 v11, v11
	v_add_f32_e32 v15, v15, v10
	v_fma_mix_f32 v14, v11, v14, v46 op_sel:[0,0,1] op_sel_hi:[0,0,1]
	s_waitcnt vmcnt(42)
	v_cvt_f32_f16_e32 v12, v47
	v_mul_f32_e32 v13, 0x3fb8aa3b, v12
	v_exp_f32_e32 v13, v13
	v_add_f32_e32 v15, v15, v12
	v_fma_mix_f32 v14, v13, v14, v47 op_sel:[0,0,1] op_sel_hi:[0,0,1]
	s_waitcnt vmcnt(41)
	v_cvt_f32_f16_e32 v10, v48
	v_mul_f32_e32 v11, 0x3fb8aa3b, v10
	v_exp_f32_e32 v11, v11
	v_add_f32_e32 v15, v15, v10
	v_fma_mix_f32 v14, v11, v14, v48 op_sel:[0,0,1] op_sel_hi:[0,0,1]
	s_waitcnt vmcnt(40)
	v_cvt_f32_f16_e32 v12, v49
	v_mul_f32_e32 v13, 0x3fb8aa3b, v12
	v_exp_f32_e32 v13, v13
	v_add_f32_e32 v15, v15, v12
	v_fma_mix_f32 v14, v13, v14, v49 op_sel:[0,0,1] op_sel_hi:[0,0,1]
	s_waitcnt vmcnt(39)
	v_cvt_f32_f16_e32 v10, v50
	v_mul_f32_e32 v11, 0x3fb8aa3b, v10
	v_exp_f32_e32 v11, v11
	v_add_f32_e32 v15, v15, v10
	v_fma_mix_f32 v14, v11, v14, v50 op_sel:[0,0,1] op_sel_hi:[0,0,1]
	s_waitcnt vmcnt(38)
	v_cvt_f32_f16_e32 v12, v51
	v_mul_f32_e32 v13, 0x3fb8aa3b, v12
	v_exp_f32_e32 v13, v13
	v_add_f32_e32 v15, v15, v12
	v_fma_mix_f32 v14, v13, v14, v51 op_sel:[0,0,1] op_sel_hi:[0,0,1]
	s_waitcnt vmcnt(37)
	v_cvt_f32_f16_e32 v10, v52
	v_mul_f32_e32 v11, 0x3fb8aa3b, v10
	v_exp_f32_e32 v11, v11
	v_add_f32_e32 v15, v15, v10
	v_fma_mix_f32 v14, v11, v14, v52 op_sel:[0,0,1] op_sel_hi:[0,0,1]
	s_waitcnt vmcnt(36)
	v_cvt_f32_f16_e32 v12, v53
	v_mul_f32_e32 v13, 0x3fb8aa3b, v12
	v_exp_f32_e32 v13, v13
	v_add_f32_e32 v15, v15, v12
	v_fma_mix_f32 v14, v13, v14, v53 op_sel:[0,0,1] op_sel_hi:[0,0,1]
	s_waitcnt vmcnt(35)
; __device__ __forceinline__ float f16_lo(unsigned w) { return (float)__builtin_bit_cast(_Float16, (unsigned short)(w & 0xffffu)); }
; __device__ __forceinline__ float f16_hi(unsigned w) { return (float)__builtin_bit_cast(_Float16, (unsigned short)(w >> 16)); }
;     __device__ __forceinline__ void operator()(const f32x4 (&acc)[2][2][4][2], const Unit& u, int wr, int wc, int fr, int fq) const {
;     ...
;           for (int b4 = 0; b4 < 4; ++b4) { unsigned w[16];
; #pragma unroll
;               for (int i = 0; i < 16; ++i) w[i] = ab[(size_t)(b4 * 16 + i) * D];
; #pragma unroll
;               for (int i = 0; i < 16; ++i) { const float la = f16_lo(w[i]); h = __expf(la) * h + f16_hi(w[i]); L += la; } }
	v_cvt_f32_f16_e32 v10, v54
	v_mul_f32_e32 v11, 0x3fb8aa3b, v10
	v_exp_f32_e32 v11, v11
	v_add_f32_e32 v15, v15, v10
	v_fma_mix_f32 v14, v11, v14, v54 op_sel:[0,0,1] op_sel_hi:[0,0,1]
	s_waitcnt vmcnt(34)
	v_cvt_f32_f16_e32 v12, v55
	v_mul_f32_e32 v13, 0x3fb8aa3b, v12
	v_exp_f32_e32 v13, v13
	v_add_f32_e32 v15, v15, v12
	v_fma_mix_f32 v14, v13, v14, v55 op_sel:[0,0,1] op_sel_hi:[0,0,1]
	s_waitcnt vmcnt(33)
	v_cvt_f32_f16_e32 v10, v56
	v_mul_f32_e32 v11, 0x3fb8aa3b, v10
	v_exp_f32_e32 v11, v11
	v_add_f32_e32 v15, v15, v10
	v_fma_mix_f32 v14, v11, v14, v56 op_sel:[0,0,1] op_sel_hi:[0,0,1]
	s_waitcnt vmcnt(32)
	v_cvt_f32_f16_e32 v12, v57
	v_mul_f32_e32 v13, 0x3fb8aa3b, v12
	v_exp_f32_e32 v13, v13
	v_add_f32_e32 v15, v15, v12
	v_fma_mix_f32 v14, v13, v14, v57 op_sel:[0,0,1] op_sel_hi:[0,0,1]
	s_waitcnt vmcnt(31)
	v_cvt_f32_f16_e32 v10, v58
	v_mul_f32_e32 v11, 0x3fb8aa3b, v10
	v_exp_f32_e32 v11, v11
	v_add_f32_e32 v15, v15, v10
	v_fma_mix_f32 v14, v11, v14, v58 op_sel:[0,0,1] op_sel_hi:[0,0,1]
	s_waitcnt vmcnt(30)
	v_cvt_f32_f16_e32 v12, v59
	v_mul_f32_e32 v13, 0x3fb8aa3b, v12
	v_exp_f32_e32 v13, v13
	v_add_f32_e32 v15, v15, v12
	v_fma_mix_f32 v14, v13, v14, v59 op_sel:[0,0,1] op_sel_hi:[0,0,1]
	s_waitcnt vmcnt(29)
	v_cvt_f32_f16_e32 v10, v60
	v_mul_f32_e32 v11, 0x3fb8aa3b, v10
	v_exp_f32_e32 v11, v11
	v_add_f32_e32 v15, v15, v10
	v_fma_mix_f32 v14, v11, v14, v60 op_sel:[0,0,1] op_sel_hi:[0,0,1]
	s_waitcnt vmcnt(28)
	v_cvt_f32_f16_e32 v12, v61
	v_mul_f32_e32 v13, 0x3fb8aa3b, v12
	v_exp_f32_e32 v13, v13
	v_add_f32_e32 v15, v15, v12
	v_fma_mix_f32 v14, v13, v14, v61 op_sel:[0,0,1] op_sel_hi:[0,0,1]
	s_waitcnt vmcnt(27)
	v_cvt_f32_f16_e32 v10, v62
	v_mul_f32_e32 v11, 0x3fb8aa3b, v10
	v_exp_f32_e32 v11, v11
	v_add_f32_e32 v15, v15, v10
	v_fma_mix_f32 v14, v11, v14, v62 op_sel:[0,0,1] op_sel_hi:[0,0,1]
	s_waitcnt vmcnt(26)
	v_cvt_f32_f16_e32 v12, v63
	v_mul_f32_e32 v13, 0x3fb8aa3b, v12
	v_exp_f32_e32 v13, v13
	v_add_f32_e32 v15, v15, v12
	v_fma_mix_f32 v14, v13, v14, v63 op_sel:[0,0,1] op_sel_hi:[0,0,1]
	s_waitcnt vmcnt(25)
	v_cvt_f32_f16_e32 v10, v64
	v_mul_f32_e32 v11, 0x3fb8aa3b, v10
	v_exp_f32_e32 v11, v11
	v_add_f32_e32 v15, v15, v10
	v_fma_mix_f32 v14, v11, v14, v64 op_sel:[0,0,1] op_sel_hi:[0,0,1]
	s_waitcnt vmcnt(24)
	v_cvt_f32_f16_e32 v12, v65
	v_mul_f32_e32 v13, 0x3fb8aa3b, v12
	v_exp_f32_e32 v13, v13
	v_add_f32_e32 v15, v15, v12
	v_fma_mix_f32 v14, v13, v14, v65 op_sel:[0,0,1] op_sel_hi:[0,0,1]
	s_waitcnt vmcnt(23)
	v_cvt_f32_f16_e32 v10, v66
	v_mul_f32_e32 v11, 0x3fb8aa3b, v10
	v_exp_f32_e32 v11, v11
	v_add_f32_e32 v15, v15, v10
	v_fma_mix_f32 v14, v11, v14, v66 op_sel:[0,0,1] op_sel_hi:[0,0,1]
	s_waitcnt vmcnt(22)
	v_cvt_f32_f16_e32 v12, v67
	v_mul_f32_e32 v13, 0x3fb8aa3b, v12
	v_exp_f32_e32 v13, v13
	v_add_f32_e32 v15, v15, v12
	v_fma_mix_f32 v14, v13, v14, v67 op_sel:[0,0,1] op_sel_hi:[0,0,1]
	s_waitcnt vmcnt(21)
	v_cvt_f32_f16_e32 v10, v68
	v_mul_f32_e32 v11, 0x3fb8aa3b, v10
	v_exp_f32_e32 v11, v11
	v_add_f32_e32 v15, v15, v10
	v_fma_mix_f32 v14, v11, v14, v68 op_sel:[0,0,1] op_sel_hi:[0,0,1]
	s_waitcnt vmcnt(20)
	v_cvt_f32_f16_e32 v12, v69
	v_mul_f32_e32 v13, 0x3fb8aa3b, v12
	v_exp_f32_e32 v13, v13
	v_add_f32_e32 v15, v15, v12
	v_fma_mix_f32 v14, v13, v14, v69 op_sel:[0,0,1] op_sel_hi:[0,0,1]
	s_waitcnt vmcnt(19)
	v_cvt_f32_f16_e32 v10, v70
	v_mul_f32_e32 v11, 0x3fb8aa3b, v10
	v_exp_f32_e32 v11, v11
	v_add_f32_e32 v15, v15, v10
	v_fma_mix_f32 v14, v11, v14, v70 op_sel:[0,0,1] op_sel_hi:[0,0,1]
	s_waitcnt vmcnt(18)
	v_cvt_f32_f16_e32 v12, v71
	v_mul_f32_e32 v13, 0x3fb8aa3b, v12
	v_exp_f32_e32 v13, v13
	v_add_f32_e32 v15, v15, v12
	v_fma_mix_f32 v14, v13, v14, v71 op_sel:[0,0,1] op_sel_hi:[0,0,1]
	s_waitcnt vmcnt(17)
	v_cvt_f32_f16_e32 v10, v72
	v_mul_f32_e32 v11, 0x3fb8aa3b, v10
	v_exp_f32_e32 v11, v11
	v_add_f32_e32 v15, v15, v10
	v_fma_mix_f32 v14, v11, v14, v72 op_sel:[0,0,1] op_sel_hi:[0,0,1]
	s_waitcnt vmcnt(16)
; __device__ __forceinline__ float f16_lo(unsigned w) { return (float)__builtin_bit_cast(_Float16, (unsigned short)(w & 0xffffu)); }
; __device__ __forceinline__ float f16_hi(unsigned w) { return (float)__builtin_bit_cast(_Float16, (unsigned short)(w >> 16)); }
;     __device__ __forceinline__ void operator()(const f32x4 (&acc)[2][2][4][2], const Unit& u, int wr, int wc, int fr, int fq) const {
;     ...
;               for (int i = 0; i < 16; ++i) w[i] = ab[(size_t)(b4 * 16 + i) * D];
; #pragma unroll
;               for (int i = 0; i < 16; ++i) { const float la = f16_lo(w[i]); h = __expf(la) * h + f16_hi(w[i]); L += la; } }
;           const size_t o = (size_t)(r0 >> 6) * 1024 + c; Ls[o] = L; Hs[o] = h; }
	v_cvt_f32_f16_e32 v12, v73
	v_mul_f32_e32 v13, 0x3fb8aa3b, v12
	v_exp_f32_e32 v13, v13
	v_add_f32_e32 v15, v15, v12
	v_fma_mix_f32 v14, v13, v14, v73 op_sel:[0,0,1] op_sel_hi:[0,0,1]
	s_waitcnt vmcnt(15)
	v_cvt_f32_f16_e32 v10, v74
	v_mul_f32_e32 v11, 0x3fb8aa3b, v10
	v_exp_f32_e32 v11, v11
	v_add_f32_e32 v15, v15, v10
	v_fma_mix_f32 v14, v11, v14, v74 op_sel:[0,0,1] op_sel_hi:[0,0,1]
	s_waitcnt vmcnt(14)
	v_cvt_f32_f16_e32 v12, v75
	v_mul_f32_e32 v13, 0x3fb8aa3b, v12
	v_exp_f32_e32 v13, v13
	v_add_f32_e32 v15, v15, v12
	v_fma_mix_f32 v14, v13, v14, v75 op_sel:[0,0,1] op_sel_hi:[0,0,1]
	s_waitcnt vmcnt(13)
	v_cvt_f32_f16_e32 v10, v76
	v_mul_f32_e32 v11, 0x3fb8aa3b, v10
	v_exp_f32_e32 v11, v11
	v_add_f32_e32 v15, v15, v10
	v_fma_mix_f32 v14, v11, v14, v76 op_sel:[0,0,1] op_sel_hi:[0,0,1]
	s_waitcnt vmcnt(12)
	v_cvt_f32_f16_e32 v12, v77
	v_mul_f32_e32 v13, 0x3fb8aa3b, v12
	v_exp_f32_e32 v13, v13
	v_add_f32_e32 v15, v15, v12
	v_fma_mix_f32 v14, v13, v14, v77 op_sel:[0,0,1] op_sel_hi:[0,0,1]
	s_waitcnt vmcnt(11)
	v_cvt_f32_f16_e32 v10, v78
	v_mul_f32_e32 v11, 0x3fb8aa3b, v10
	v_exp_f32_e32 v11, v11
	v_add_f32_e32 v15, v15, v10
	v_fma_mix_f32 v14, v11, v14, v78 op_sel:[0,0,1] op_sel_hi:[0,0,1]
	s_waitcnt vmcnt(10)
	v_cvt_f32_f16_e32 v12, v79
	v_mul_f32_e32 v13, 0x3fb8aa3b, v12
	v_exp_f32_e32 v13, v13
	v_add_f32_e32 v15, v15, v12
	v_fma_mix_f32 v14, v13, v14, v79 op_sel:[0,0,1] op_sel_hi:[0,0,1]
	s_waitcnt vmcnt(9)
	v_cvt_f32_f16_e32 v10, v80
	v_mul_f32_e32 v11, 0x3fb8aa3b, v10
	v_exp_f32_e32 v11, v11
	v_add_f32_e32 v15, v15, v10
	v_fma_mix_f32 v14, v11, v14, v80 op_sel:[0,0,1] op_sel_hi:[0,0,1]
	s_waitcnt vmcnt(8)
	v_cvt_f32_f16_e32 v12, v81
	v_mul_f32_e32 v13, 0x3fb8aa3b, v12
	v_exp_f32_e32 v13, v13
	v_add_f32_e32 v15, v15, v12
	v_fma_mix_f32 v14, v13, v14, v81 op_sel:[0,0,1] op_sel_hi:[0,0,1]
	s_waitcnt vmcnt(7)
	v_cvt_f32_f16_e32 v10, v82
	v_mul_f32_e32 v11, 0x3fb8aa3b, v10
	v_exp_f32_e32 v11, v11
	v_add_f32_e32 v15, v15, v10
	v_fma_mix_f32 v14, v11, v14, v82 op_sel:[0,0,1] op_sel_hi:[0,0,1]
	s_waitcnt vmcnt(6)
	v_cvt_f32_f16_e32 v12, v83
	v_mul_f32_e32 v13, 0x3fb8aa3b, v12
	v_exp_f32_e32 v13, v13
	v_add_f32_e32 v15, v15, v12
	v_fma_mix_f32 v14, v13, v14, v83 op_sel:[0,0,1] op_sel_hi:[0,0,1]
	s_waitcnt vmcnt(5)
	v_cvt_f32_f16_e32 v10, v84
	v_mul_f32_e32 v11, 0x3fb8aa3b, v10
	v_exp_f32_e32 v11, v11
	v_add_f32_e32 v15, v15, v10
	v_fma_mix_f32 v14, v11, v14, v84 op_sel:[0,0,1] op_sel_hi:[0,0,1]
	s_waitcnt vmcnt(4)
	v_cvt_f32_f16_e32 v12, v85
	v_mul_f32_e32 v13, 0x3fb8aa3b, v12
	v_exp_f32_e32 v13, v13
	v_add_f32_e32 v15, v15, v12
	v_fma_mix_f32 v14, v13, v14, v85 op_sel:[0,0,1] op_sel_hi:[0,0,1]
	s_waitcnt vmcnt(3)
	v_cvt_f32_f16_e32 v10, v86
	v_mul_f32_e32 v11, 0x3fb8aa3b, v10
	v_exp_f32_e32 v11, v11
	v_add_f32_e32 v15, v15, v10
	v_fma_mix_f32 v14, v11, v14, v86 op_sel:[0,0,1] op_sel_hi:[0,0,1]
	s_waitcnt vmcnt(2)
	v_cvt_f32_f16_e32 v12, v87
	v_mul_f32_e32 v13, 0x3fb8aa3b, v12
	v_exp_f32_e32 v13, v13
	v_add_f32_e32 v15, v15, v12
	v_fma_mix_f32 v14, v13, v14, v87 op_sel:[0,0,1] op_sel_hi:[0,0,1]
	s_waitcnt vmcnt(1)
	v_cvt_f32_f16_e32 v10, v88
	v_mul_f32_e32 v11, 0x3fb8aa3b, v10
	v_exp_f32_e32 v11, v11
	v_add_f32_e32 v15, v15, v10
	v_fma_mix_f32 v14, v11, v14, v88 op_sel:[0,0,1] op_sel_hi:[0,0,1]
	s_waitcnt vmcnt(0)
	v_cvt_f32_f16_e32 v12, v89
	v_mul_f32_e32 v13, 0x3fb8aa3b, v12
	v_exp_f32_e32 v13, v13
	v_add_f32_e32 v15, v15, v12
	v_fma_mix_f32 v14, v13, v14, v89 op_sel:[0,0,1] op_sel_hi:[0,0,1]
	v_mov_b32_e32 v6, v14
	v_mov_b32_e32 v7, v15
	s_mov_b32 s0, 0x3f000
	s_and_b64 vcc, exec, s[4:5]
	v_ashrrev_i32_e32 v5, 31, v4
	v_lshlrev_b64 v[4:5], 10, v[4:5]
	v_lshl_add_u64 v[2:3], v[4:5], 0, v[2:3]
	v_lshlrev_b64 v[2:3], 2, v[2:3]
	v_lshl_add_u64 v[4:5], s[74:75], 0, v[2:3]
	v_lshl_add_u64 v[2:3], s[22:23], 0, v[2:3]
	global_store_dword v[4:5], v7, off
	global_store_dword v[2:3], v6, off
	s_cbranch_vccnz .LBB0_172
	s_andn2_b64 vcc, exec, s[18:19]
	s_cbranch_vccnz .LBB0_171
	s_barrier
	s_branch .LBB0_171
